# attention loop: row-max and row-sum serial chains as 4-way trees; K/V LDS-write addresses kept in registers across the loop
# baseline (speedup 1.0000x reference)
; __device__ __forceinline__ void finishSM(f32x16& p0, f32x16& p1, float alpha, float& l_reg, bf16x8& pa0, bf16x8& pa1, bf16x8& pa2, bf16x8& pa3) {
;     for (int r = 0; r < 16; ++r) p1[r] = __builtin_amdgcn_exp2f(p1[r]);
;     float ps = 0; for (int r = 0; r < 16; ++r) ps += p0[r]; for (int r = 0; r < 16; ++r) ps += p1[r];
;     { auto rr = __builtin_amdgcn_permlane32_swap(__float_as_uint(ps), __float_as_uint(ps), false, false);
;       ps = __uint_as_float(rr[0]) + __uint_as_float(rr[1]); }
;     l_reg = l_reg * alpha + ps;
;     ...
;     PK4(p0, 0, pa0); PK4(p0, 8, pa1); PK4(p1, 0, pa2); PK4(p1, 8, pa3);
;     ...
; }
; template <int KB>
; __device__ __forceinline__ void qkt(f32x16& p0, f32x16& p1, const char* K_lds, const char* cbt, int r32, int hi, const bf16x8* qr) {
;     { const u32x2 e0 = *(const u32x2*)(cbt), e1 = *(const u32x2*)(cbt + 32 * 8);
;       const unsigned c0 = hi ? 0u : 0x3F803F80u, c1 = hi ? 0u : 0x00003F80u;
;       const u32x4 k0 = {e0.x, e0.y, e0.x, e0.y}, k1 = {e1.x, e1.y, e1.x, e1.y}, q1 = {c0, c1, 0u, 0u};
;       p0 = __builtin_amdgcn_mfma_f32_32x32x16_bf16(__builtin_bit_cast(bf16x8, k0), __builtin_bit_cast(bf16x8, q1), f32x16{}, 0, 0, 0);
;       p1 = __builtin_amdgcn_mfma_f32_32x32x16_bf16(__builtin_bit_cast(bf16x8, k1), __builtin_bit_cast(bf16x8, q1), f32x16{}, 0, 0, 0); }
;     const char* kb[4];
; #pragma unroll
;     for (int dd = 0; dd < 4; ++dd) kb[dd] = K_lds + KB * SHM_K + KSWZ(r32, (dd * 16 + hi * 8) * 2);
; #pragma unroll
;     for (int d0 = 0; d0 < 8; ++d0) { const char* a = kb[d0 & 3] + (d0 >> 2) * 128;
;         bf16x8 b0 = *reinterpret_cast<const bf16x8*>(a);
;         bf16x8 b1 = *reinterpret_cast<const bf16x8*>(a + 32 * 256);
;         p0 = __builtin_amdgcn_mfma_f32_32x32x16_bf16(b0, qr[d0], p0, 0, 0, 0);
;         p1 = __builtin_amdgcn_mfma_f32_32x32x16_bf16(b1, qr[d0], p1, 0, 0, 0); }
; }
.LBB0_230:
	v_add_u32_e32 v102, s89, v192
	v_add_u32_e32 v66, 0xffffff81, v102
	v_ashrrev_i32_e32 v67, 31, v66
	v_add_u32_e32 v70, 0xffffffa1, v102
	v_lshlrev_b64 v[66:67], 11, v[66:67]
	v_ashrrev_i32_e32 v71, 31, v70
	v_lshl_add_u64 v[68:69], v[188:189], 0, v[66:67]
	v_lshlrev_b64 v[70:71], 11, v[70:71]
	v_lshl_add_u64 v[66:67], v[190:191], 0, v[66:67]
	v_lshl_add_u64 v[72:73], v[188:189], 0, v[70:71]
	global_load_dwordx4 v[174:177], v[68:69], off
	global_load_dwordx4 v[170:173], v[72:73], off
	v_lshl_add_u64 v[68:69], v[190:191], 0, v[70:71]
	global_load_dwordx4 v[166:169], v[66:67], off
	global_load_dwordx4 v[178:181], v[68:69], off
	ds_read2_b64 v[66:69], v215 offset0:64 offset1:96
	v_exp_f32_e32 v103, v126
	v_exp_f32_e32 v108, v127
	v_exp_f32_e32 v109, v124
	v_exp_f32_e32 v110, v125
	s_waitcnt lgkmcnt(0)
	v_mov_b32_e32 v70, v66
	v_mov_b32_e32 v71, v67
	v_mov_b32_e32 v72, v66
	v_mov_b32_e32 v73, v67
	v_mov_b32_e32 v66, v68
	v_mov_b32_e32 v67, v69
	v_mfma_f32_32x32x16_bf16 v[86:101], v[70:73], v[162:165], 0
	v_exp_f32_e32 v111, v120
	v_exp_f32_e32 v112, v121
	v_exp_f32_e32 v113, v116
	v_exp_f32_e32 v116, v117
	v_exp_f32_e32 v114, v114
	v_exp_f32_e32 v115, v115
	v_exp_f32_e32 v117, v128
	v_mfma_f32_32x32x16_bf16 v[70:85], v[66:69], v[162:165], 0
	ds_read_b128 v[66:69], v205 offset:49152
	ds_read_b128 v[104:107], v205 offset:57344
	v_exp_f32_e32 v120, v129
	v_exp_f32_e32 v121, v122
	v_exp_f32_e32 v122, v123
	v_exp_f32_e32 v118, v118
	v_exp_f32_e32 v119, v119
	s_waitcnt lgkmcnt(1)
	v_mfma_f32_32x32x16_bf16 v[86:101], v[66:69], v[158:161], v[86:101]
	s_waitcnt lgkmcnt(0)
	v_mfma_f32_32x32x16_bf16 v[70:85], v[104:107], v[158:161], v[70:85]
	ds_read_b128 v[66:69], v206 offset:49152
	ds_read_b128 v[104:107], v206 offset:57344
	s_waitcnt lgkmcnt(1)
	v_mfma_f32_32x32x16_bf16 v[86:101], v[66:69], v[154:157], v[86:101]
	s_waitcnt lgkmcnt(0)
	v_mfma_f32_32x32x16_bf16 v[70:85], v[104:107], v[154:157], v[70:85]
	ds_read_b128 v[66:69], v207 offset:49152
	ds_read_b128 v[104:107], v207 offset:57344
	s_waitcnt lgkmcnt(1)
	v_mfma_f32_32x32x16_bf16 v[86:101], v[66:69], v[150:153], v[86:101]
	s_waitcnt lgkmcnt(0)
	v_mfma_f32_32x32x16_bf16 v[70:85], v[104:107], v[150:153], v[70:85]
	ds_read_b128 v[66:69], v208 offset:49152
	ds_read_b128 v[104:107], v208 offset:57344
	s_waitcnt lgkmcnt(1)
	v_mfma_f32_32x32x16_bf16 v[86:101], v[66:69], v[146:149], v[86:101]
	s_waitcnt lgkmcnt(0)
	v_mfma_f32_32x32x16_bf16 v[70:85], v[104:107], v[146:149], v[70:85]
	ds_read_b128 v[66:69], v205 offset:49280
	ds_read_b128 v[104:107], v205 offset:57472
	s_waitcnt lgkmcnt(1)
	v_mfma_f32_32x32x16_bf16 v[86:101], v[66:69], v[142:145], v[86:101]
	s_waitcnt lgkmcnt(0)
	v_mfma_f32_32x32x16_bf16 v[70:85], v[104:107], v[142:145], v[70:85]
	ds_read_b128 v[66:69], v206 offset:49280
	ds_read_b128 v[104:107], v206 offset:57472
	s_waitcnt lgkmcnt(1)
	v_mfma_f32_32x32x16_bf16 v[86:101], v[66:69], v[138:141], v[86:101]
	s_waitcnt lgkmcnt(0)
	v_mfma_f32_32x32x16_bf16 v[70:85], v[104:107], v[138:141], v[70:85]
	ds_read_b128 v[66:69], v207 offset:49280
	ds_read_b128 v[104:107], v207 offset:57472
	s_waitcnt lgkmcnt(1)
	v_mfma_f32_32x32x16_bf16 v[86:101], v[66:69], v[134:137], v[86:101]
	s_waitcnt lgkmcnt(0)
	v_mfma_f32_32x32x16_bf16 v[70:85], v[104:107], v[134:137], v[70:85]
	ds_read_b128 v[66:69], v208 offset:49280
	ds_read_b128 v[104:107], v208 offset:57472
	s_waitcnt lgkmcnt(1)
	v_mfma_f32_32x32x16_bf16 v[86:101], v[66:69], v[130:133], v[86:101]
	v_add_f32_e32 v66, v234, v231
	v_add_f32_e32 v67, v236, v233
	v_add_f32_e32 v68, v232, v229
	v_add_f32_e32 v69, v235, v230
	v_add_f32_e32 v66, v226, v66
	v_add_f32_e32 v67, v228, v67
	v_add_f32_e32 v68, v225, v68
	v_add_f32_e32 v69, v227, v69
	v_add_f32_e32 v66, v222, v66
	v_add_f32_e32 v67, v224, v67
	v_add_f32_e32 v68, v221, v68
	v_add_f32_e32 v69, v223, v69
	v_add_f32_e32 v66, v103, v66
	v_add_f32_e32 v67, v108, v67
	v_add_f32_e32 v68, v109, v68
	v_add_f32_e32 v69, v110, v69
	v_add_f32_e32 v66, v111, v66
	v_add_f32_e32 v67, v112, v67
	v_add_f32_e32 v68, v113, v68
	v_add_f32_e32 v69, v116, v69
	v_add_f32_e32 v66, v114, v66
	v_add_f32_e32 v67, v115, v67
	s_waitcnt lgkmcnt(0)
	v_mfma_f32_32x32x16_bf16 v[70:85], v[104:107], v[130:133], v[70:85]
	v_add_f32_e32 v68, v117, v68
	v_add_f32_e32 v69, v120, v69
	v_add_f32_e32 v66, v121, v66
	v_add_f32_e32 v67, v122, v67
	v_add_f32_e32 v68, v118, v68
	v_add_f32_e32 v69, v119, v69
	v_add_f32_e32 v66, v66, v67
	v_add_f32_e32 v68, v68, v69
	v_add_f32_e32 v218, v66, v68
	v_mov_b32_e32 v219, v218
	s_nop 1
	v_permlane32_swap_b32_e32 v218, v219
	v_cvt_pk_bf16_f32 v66, v234, v236
	v_cvt_pk_bf16_f32 v67, v232, v235
	v_cvt_pk_bf16_f32 v68, v231, v233
	v_cvt_pk_bf16_f32 v69, v229, v230
	v_cvt_pk_bf16_f32 v104, v226, v228
	v_cvt_pk_bf16_f32 v105, v225, v227
	v_cvt_pk_bf16_f32 v106, v222, v224
	v_cvt_pk_bf16_f32 v107, v221, v223
	v_cvt_pk_bf16_f32 v108, v103, v108
	v_cvt_pk_bf16_f32 v109, v109, v110
	v_cvt_pk_bf16_f32 v110, v111, v112
	v_cvt_pk_bf16_f32 v111, v113, v116
	v_cvt_pk_bf16_f32 v112, v114, v115
	v_cvt_pk_bf16_f32 v113, v117, v120
	v_cvt_pk_bf16_f32 v114, v121, v122
	v_cvt_pk_bf16_f32 v115, v118, v119
	s_nop 0
	v_permlane32_swap_b32_e32 v66, v68
	v_permlane32_swap_b32_e32 v67, v69
	v_permlane32_swap_b32_e32 v104, v106
	v_permlane32_swap_b32_e32 v105, v107
	v_permlane32_swap_b32_e32 v108, v110
	v_permlane32_swap_b32_e32 v109, v111
	v_permlane32_swap_b32_e32 v112, v114
	v_permlane32_swap_b32_e32 v113, v115
	ds_read_b64_tr_b16 v[116:117], v199 offset:0
	ds_read_b64_tr_b16 v[118:119], v199 offset:0x800
	ds_read_b64_tr_b16 v[120:121], v199 offset:0x200
	ds_read_b64_tr_b16 v[122:123], v199 offset:0xa00
	ds_read_b64_tr_b16 v[124:125], v199 offset:0x1000
	ds_read_b64_tr_b16 v[126:127], v199 offset:0x1800
	ds_read_b64_tr_b16 v[220:221], v199 offset:0x1200
	ds_read_b64_tr_b16 v[222:223], v199 offset:0x1a00
	s_waitcnt lgkmcnt(0)
; __device__ __forceinline__ void mask_tile(f32x16& p0, f32x16& p1, int dq, unsigned W) {
;     const float NEG = -__builtin_inff();
; #pragma unroll
;     for (int r = 0; r < 16; ++r) {
;         const int c = (r & 3) + 8 * (r >> 2);
;         if ((unsigned)(dq - c) >= W) p0[r] = NEG;
;         if ((unsigned)(dq - c - 32) >= W) p1[r] = NEG;
;     }
; }
; template <int VB>
; __device__ __forceinline__ void pv_tile(f32x16* o, int vb0, bf16x8 pa0, bf16x8 pa1, bf16x8 pa2, bf16x8 pa3) {
;     ...
;     PV_R(0, 0, pa0, pa1); PV_R(0, 2, pa2, pa3); PV_R(2, 0, pa0, pa1); PV_R(2, 2, pa2, pa3);
;     ...
; }
	s_nop 0
	v_mfma_f32_32x32x16_bf16 v[2:17], v[66:69], v[116:119], v[2:17]
	ds_read_b64_tr_b16 v[116:117], v199 offset:0x2000
	ds_read_b64_tr_b16 v[118:119], v199 offset:0x2800
	v_mfma_f32_32x32x16_bf16 v[50:65], v[66:69], v[120:123], v[50:65]
	ds_read_b64_tr_b16 v[120:121], v199 offset:0x2200
	ds_read_b64_tr_b16 v[122:123], v199 offset:0x2a00
	v_mfma_f32_32x32x16_bf16 v[2:17], v[104:107], v[124:127], v[2:17]
	ds_read_b64_tr_b16 v[124:125], v199 offset:0x3000
	ds_read_b64_tr_b16 v[126:127], v199 offset:0x3800
	ds_read_b64_tr_b16 v[224:225], v199 offset:0x3200
	ds_read_b64_tr_b16 v[226:227], v199 offset:0x3a00
	s_waitcnt lgkmcnt(0)
	v_mfma_f32_32x32x16_bf16 v[50:65], v[104:107], v[220:223], v[50:65]
	v_mfma_f32_32x32x16_bf16 v[2:17], v[108:111], v[116:119], v[2:17]
	ds_read_b64_tr_b16 v[116:117], v199 offset:0x400
	ds_read_b64_tr_b16 v[118:119], v199 offset:0xc00
	v_mfma_f32_32x32x16_bf16 v[50:65], v[108:111], v[120:123], v[50:65]
	ds_read_b64_tr_b16 v[120:121], v199 offset:0x600
	ds_read_b64_tr_b16 v[122:123], v199 offset:0xe00
	v_mfma_f32_32x32x16_bf16 v[2:17], v[112:115], v[124:127], v[2:17]
	ds_read_b64_tr_b16 v[124:125], v199 offset:0x1400
	ds_read_b64_tr_b16 v[126:127], v199 offset:0x1c00
	ds_read_b64_tr_b16 v[220:221], v199 offset:0x1600
	ds_read_b64_tr_b16 v[222:223], v199 offset:0x1e00
	s_waitcnt lgkmcnt(0)
	v_mfma_f32_32x32x16_bf16 v[50:65], v[112:115], v[224:227], v[50:65]
	v_mfma_f32_32x32x16_bf16 v[34:49], v[66:69], v[116:119], v[34:49]
	v_mfma_f32_32x32x16_bf16 v[18:33], v[66:69], v[120:123], v[18:33]
	ds_read_b64_tr_b16 v[66:67], v199 offset:0x2400
	ds_read_b64_tr_b16 v[68:69], v199 offset:0x2c00
	ds_read_b64_tr_b16 v[116:117], v199 offset:0x2600
	ds_read_b64_tr_b16 v[118:119], v199 offset:0x2e00
	ds_read_b64_tr_b16 v[120:121], v199 offset:0x3400
	ds_read_b64_tr_b16 v[122:123], v199 offset:0x3c00
	v_mfma_f32_32x32x16_bf16 v[34:49], v[104:107], v[124:127], v[34:49]
	ds_read_b64_tr_b16 v[124:125], v199 offset:0x3600
	ds_read_b64_tr_b16 v[126:127], v199 offset:0x3e00
	s_waitcnt lgkmcnt(0)
	v_mfma_f32_32x32x16_bf16 v[18:33], v[104:107], v[220:223], v[18:33]
	v_mfma_f32_32x32x16_bf16 v[34:49], v[108:111], v[66:69], v[34:49]
	s_cmp_le_i32 s89, s76
	v_mfma_f32_32x32x16_bf16 v[18:33], v[108:111], v[116:119], v[18:33]
	v_mfma_f32_32x32x16_bf16 v[34:49], v[112:115], v[120:123], v[34:49]
	v_mfma_f32_32x32x16_bf16 v[18:33], v[112:115], v[124:127], v[18:33]
	s_cbranch_scc1 .LBB0_232
	v_subrev_u32_e32 v66, 64, v216
	v_cmp_gt_u32_e32 vcc, 2.0, v66
	v_add_u32_e32 v66, 0xbfffffa0, v216
	s_nop 0
	v_cndmask_b32_e32 v86, v209, v86, vcc
	v_cmp_lt_u32_e32 vcc, s17, v66
	v_add_u32_e32 v66, 0xbfffffbf, v216
	s_nop 0
	v_cndmask_b32_e32 v70, v209, v70, vcc
	v_cmp_lt_u32_e32 vcc, s17, v66
	v_add_u32_e32 v66, 0xbfffff9f, v216
	s_nop 0
	v_cndmask_b32_e32 v87, v209, v87, vcc
	v_cmp_lt_u32_e32 vcc, s17, v66
	v_add_u32_e32 v66, 0xbfffffbe, v216
	s_nop 0
	v_cndmask_b32_e32 v71, v209, v71, vcc
	v_cmp_lt_u32_e32 vcc, s17, v66
	v_add_u32_e32 v66, 0xbfffff9e, v216
	s_nop 0
	v_cndmask_b32_e32 v88, v209, v88, vcc
	v_cmp_lt_u32_e32 vcc, s17, v66
	v_add_u32_e32 v66, 0xbfffffbd, v216
	s_nop 0
	v_cndmask_b32_e32 v72, v209, v72, vcc
	v_cmp_lt_u32_e32 vcc, s17, v66
	v_add_u32_e32 v66, 0xbfffff9d, v216
	s_nop 0
	v_cndmask_b32_e32 v89, v209, v89, vcc
	v_cmp_lt_u32_e32 vcc, s17, v66
	v_add_u32_e32 v66, 0xbfffffb8, v216
	s_nop 0
	v_cndmask_b32_e32 v73, v209, v73, vcc
	v_cmp_lt_u32_e32 vcc, s17, v66
	v_add_u32_e32 v66, 0xbfffff98, v216
	s_nop 0
	v_cndmask_b32_e32 v90, v209, v90, vcc
	v_cmp_lt_u32_e32 vcc, s17, v66
	v_add_u32_e32 v66, 0xbfffffb7, v216
	s_nop 0
	v_cndmask_b32_e32 v74, v209, v74, vcc
	v_cmp_lt_u32_e32 vcc, s17, v66
	v_add_u32_e32 v66, 0xbfffff97, v216
	s_nop 0
	v_cndmask_b32_e32 v91, v209, v91, vcc
	v_cmp_lt_u32_e32 vcc, s17, v66
	v_add_u32_e32 v66, 0xbfffffb6, v216
	s_nop 0
	v_cndmask_b32_e32 v75, v209, v75, vcc
	v_cmp_lt_u32_e32 vcc, s17, v66
	v_add_u32_e32 v66, 0xbfffff96, v216
	s_nop 0
	v_cndmask_b32_e32 v92, v209, v92, vcc
	v_cmp_lt_u32_e32 vcc, s17, v66
	v_add_u32_e32 v66, 0xbfffffb5, v216
	s_nop 0
	v_cndmask_b32_e32 v76, v209, v76, vcc
	v_cmp_lt_u32_e32 vcc, s17, v66
	v_add_u32_e32 v66, 0xbfffff95, v216
	s_nop 0
	v_cndmask_b32_e32 v93, v209, v93, vcc
	v_cmp_lt_u32_e32 vcc, s17, v66
	v_add_u32_e32 v66, 0xbfffffb0, v216
	s_nop 0
	v_cndmask_b32_e32 v77, v209, v77, vcc
	v_cmp_lt_u32_e32 vcc, s17, v66
	v_add_u32_e32 v66, 0xbfffff90, v216
	s_nop 0
	v_cndmask_b32_e32 v94, v209, v94, vcc
	v_cmp_lt_u32_e32 vcc, s17, v66
	v_add_u32_e32 v66, 0xbfffffaf, v216
	s_nop 0
	v_cndmask_b32_e32 v78, v209, v78, vcc
	v_cmp_lt_u32_e32 vcc, s17, v66
	v_add_u32_e32 v66, 0xbfffff8f, v216
	s_nop 0
	v_cndmask_b32_e32 v95, v209, v95, vcc
	v_cmp_lt_u32_e32 vcc, s17, v66
	v_add_u32_e32 v66, 0xbfffffae, v216
	s_nop 0
	v_cndmask_b32_e32 v79, v209, v79, vcc
	v_cmp_lt_u32_e32 vcc, s17, v66
	v_add_u32_e32 v66, 0xbfffff8e, v216
	s_nop 0
	v_cndmask_b32_e32 v96, v209, v96, vcc
	v_cmp_lt_u32_e32 vcc, s17, v66
	v_add_u32_e32 v66, 0xbfffffad, v216
	s_nop 0
	v_cndmask_b32_e32 v80, v209, v80, vcc
	v_cmp_lt_u32_e32 vcc, s17, v66
	v_add_u32_e32 v66, 0xbfffff8d, v216
	s_nop 0
	v_cndmask_b32_e32 v97, v209, v97, vcc
	v_cmp_lt_u32_e32 vcc, s17, v66
	v_add_u32_e32 v66, 0xbfffffa8, v216
	s_nop 0
	v_cndmask_b32_e32 v81, v209, v81, vcc
	v_cmp_lt_u32_e32 vcc, s17, v66
	v_add_u32_e32 v66, 0xbfffff88, v216
	s_nop 0
	v_cndmask_b32_e32 v98, v209, v98, vcc
	v_cmp_lt_u32_e32 vcc, s17, v66
	v_add_u32_e32 v66, 0xbfffffa7, v216
	s_nop 0
	v_cndmask_b32_e32 v82, v209, v82, vcc
	v_cmp_lt_u32_e32 vcc, s17, v66
	v_add_u32_e32 v66, 0xbfffff87, v216
	s_nop 0
	v_cndmask_b32_e32 v99, v209, v99, vcc
	v_cmp_lt_u32_e32 vcc, s17, v66
	v_add_u32_e32 v66, 0xbfffffa6, v216
	s_nop 0
	v_cndmask_b32_e32 v83, v209, v83, vcc
	v_cmp_lt_u32_e32 vcc, s17, v66
	v_add_u32_e32 v66, 0xbfffff86, v216
	s_nop 0
	v_cndmask_b32_e32 v100, v209, v100, vcc
	v_cmp_lt_u32_e32 vcc, s17, v66
	v_add_u32_e32 v66, 0xbfffffa5, v216
	s_nop 0
	v_cndmask_b32_e32 v84, v209, v84, vcc
	v_cmp_lt_u32_e32 vcc, s17, v66
	v_add_u32_e32 v66, 0xbfffff85, v216
	s_nop 0
	v_cndmask_b32_e32 v101, v209, v101, vcc
	v_cmp_lt_u32_e32 vcc, s17, v66
	s_nop 1
	v_cndmask_b32_e32 v85, v209, v85, vcc
; #define SBAR() __builtin_amdgcn_sched_barrier(0)
; #define VMW() asm volatile("s_waitcnt vmcnt(0)" ::: "memory")
; #define SLOAD_H(Kp, Vp, k0) do { S.st_v0 = load8(ROWK(Vp, k0, sr)); S.st_v1 = load8(ROWK(Vp, k0, 32 + sr));              \
;                          S.st_k0 = load8(ROWK(Kp, k0, sr)); S.st_k1 = load8(ROWK(Kp, k0, 32 + sr)); } while (0)
; #define SWRITE_HV(bf) do { OPQ_TID(); const int vst0_ = v_st(sr_, sc_), vst1_ = v_st(32 + sr_, sc_); *(bf16x8*)(V_lds + (bf) * SHM_V + vst0_) = S.st_v0; *(bf16x8*)(V_lds + (bf) * SHM_V + vst1_) = S.st_v1; } while (0)
; #define SWRITE_H(bf) do { SWRITE_HV(bf); SWRITE_HK(bf); } while (0)
; #define MASKT(P0_, P1_, t) do { const int kb_ = KBASE(t); if (kb_ + KVBLK - 1 > qlo) mask_tile(P0_, P1_, qm - kb_, (unsigned)W); } while (0)
; __device__ __forceinline__ void partialSM(f32x16& p0, f32x16& p1, float& m_reg, float& mn, float& alpha) {
;     float pmax = p0[0]; for (int r = 1; r < 16; ++r) pmax = fmaxf(pmax, p0[r]); for (int r = 0; r < 16; ++r) pmax = fmaxf(pmax, p1[r]);
;     { auto rr = __builtin_amdgcn_permlane32_swap(__float_as_uint(pmax), __float_as_uint(pmax), false, false);
;       pmax = fmaxf(__uint_as_float(rr[0]), __uint_as_float(rr[1])); }
;     constexpr float C2 = 1.4426950408889634f * SCALE;
;     if (__builtin_expect(__all((pmax - m_reg) * SCALE <= THR), 1)) { mn = m_reg; alpha = 1.f; }
;     else { mn = fmaxf(m_reg, pmax); alpha = __builtin_amdgcn_exp2f((m_reg - mn) * C2); m_reg = mn; }
; __device__ __forceinline__ void fox_block(const BlockRef& cur, const BlockRef& nxt, char* lds, char* cbcur, char* cbnxt, Seam& S) {
;     ...
;     constexpr int NQL = 8;
;     ...
;     f32x16 pA0, pA1, pB0, pB1; float mnA, mnB, alA, alB; bf16x8 pa0, pa1, pa2, pa3;
;     SWRITE_HV(0); SBAR();
;     if (NT > 1) { SLOAD_H(Kh, Vh, KBASE(1)); }
;     SBAR(); qkt<0>(pA0, pA1, K_lds, cbl + 8 * KBASE(0), r32, hi, S.qr);
;     MASKT(pA0, pA1, 0); partialSM(pA0, pA1, m_reg, mnA, alA);
;     if (NT > 1) { VMW(); SWRITE_H(1); }
;     __syncthreads();
.LBB0_232:
	v_max3_f32 v66, v86, v87, v88
	v_max3_f32 v67, v89, v90, v91
	v_max3_f32 v68, v92, v93, v94
	v_max3_f32 v69, v95, v96, v97
	v_max3_f32 v66, v66, v98, v99
	v_max3_f32 v67, v67, v100, v101
	v_max3_f32 v68, v68, v70, v71
	v_max3_f32 v69, v69, v72, v73
	v_max3_f32 v66, v66, v74, v75
	v_max3_f32 v67, v67, v76, v77
	v_max3_f32 v68, v68, v78, v79
	v_max3_f32 v69, v69, v80, v81
	v_max3_f32 v66, v66, v82, v83
	v_max3_f32 v67, v67, v84, v85
	v_max3_f32 v66, v66, v67, v68
	v_max_f32_e32 v66, v66, v69
	v_mov_b32_e32 v67, v66
	s_nop 1
	v_permlane32_swap_b32_e32 v66, v67
	v_max_f32_e32 v67, v67, v67
	v_max_f32_e32 v66, v66, v66
	v_max_f32_e32 v66, v66, v67
	v_max_f32_e32 v68, v217, v217
	v_sub_f32_e32 v67, v66, v217
	v_max_f32_e32 v66, v68, v66
	v_sub_f32_e32 v68, v217, v66
	v_mul_f32_e32 v68, 0x3e0293ee, v68
	v_mul_f32_e32 v67, 0x3db504f3, v67
	v_exp_f32_e32 v68, v68
	v_cmp_ge_f32_e32 vcc, s78, v67
	s_cmp_eq_u64 vcc, exec
	s_cselect_b64 s[4:5], -1, 0
	v_cndmask_b32_e64 v220, v68, 1.0, s[4:5]
	s_barrier
	s_waitcnt vmcnt(0)
	v_cmp_gt_f32_e32 vcc, 1.0, v220
	s_waitcnt vmcnt(3)
	ds_write_b128 v1, v[174:177] offset:0
	s_waitcnt vmcnt(2)
	ds_write_b128 v1, v[170:173] offset:8192
	s_waitcnt vmcnt(1)
	ds_write_b128 v201, v[166:169] offset:32768
	s_waitcnt vmcnt(0)
	ds_write_b128 v201, v[178:181] offset:40960
	s_cbranch_vccz .LBB0_236
	s_and_saveexec_b64 s[74:75], s[6:7]
	ds_write_b32 v212, v220 offset:128
	s_or_b64 exec, exec, s[74:75]
	s_waitcnt lgkmcnt(0)
	ds_read_b128 v[104:107], v211 offset:224
	ds_read_b128 v[108:111], v211 offset:192
	ds_read_b128 v[112:115], v211 offset:160
	ds_read_b128 v[116:119], v211 offset:128
	s_waitcnt lgkmcnt(3)
	v_pk_mul_f32 v[16:17], v[16:17], v[106:107]
	s_waitcnt lgkmcnt(2)
	v_pk_mul_f32 v[12:13], v[12:13], v[110:111]
	s_waitcnt lgkmcnt(1)
	v_pk_mul_f32 v[8:9], v[8:9], v[114:115]
	s_waitcnt lgkmcnt(0)
	v_pk_mul_f32 v[4:5], v[4:5], v[118:119]
	v_pk_mul_f32 v[14:15], v[14:15], v[104:105]
	v_pk_mul_f32 v[10:11], v[10:11], v[108:109]
	v_pk_mul_f32 v[6:7], v[6:7], v[112:113]
	v_pk_mul_f32 v[2:3], v[2:3], v[116:117]
	v_pk_mul_f32 v[64:65], v[64:65], v[106:107]
	v_pk_mul_f32 v[60:61], v[60:61], v[110:111]
	v_pk_mul_f32 v[56:57], v[56:57], v[114:115]
	v_pk_mul_f32 v[52:53], v[52:53], v[118:119]
	v_pk_mul_f32 v[62:63], v[62:63], v[104:105]
	v_pk_mul_f32 v[58:59], v[58:59], v[108:109]
	v_pk_mul_f32 v[54:55], v[54:55], v[112:113]
	v_pk_mul_f32 v[50:51], v[50:51], v[116:117]
	v_pk_mul_f32 v[48:49], v[48:49], v[106:107]
	v_pk_mul_f32 v[44:45], v[44:45], v[110:111]
	v_pk_mul_f32 v[40:41], v[40:41], v[114:115]
	v_pk_mul_f32 v[36:37], v[36:37], v[118:119]
	v_pk_mul_f32 v[46:47], v[46:47], v[104:105]
	v_pk_mul_f32 v[42:43], v[42:43], v[108:109]
	v_pk_mul_f32 v[38:39], v[38:39], v[112:113]
	v_pk_mul_f32 v[34:35], v[34:35], v[116:117]
	v_pk_mul_f32 v[32:33], v[32:33], v[106:107]
	v_pk_mul_f32 v[28:29], v[28:29], v[110:111]
	v_pk_mul_f32 v[24:25], v[24:25], v[114:115]
	v_pk_mul_f32 v[20:21], v[20:21], v[118:119]
	v_pk_mul_f32 v[30:31], v[30:31], v[104:105]
	v_pk_mul_f32 v[26:27], v[26:27], v[108:109]
	v_pk_mul_f32 v[22:23], v[22:23], v[112:113]
	v_pk_mul_f32 v[18:19], v[18:19], v[116:117]

; __device__ __forceinline__ void partialSM(f32x16& p0, f32x16& p1, float& m_reg, float& mn, float& alpha) {
;     float pmax = p0[0]; for (int r = 1; r < 16; ++r) pmax = fmaxf(pmax, p0[r]); for (int r = 0; r < 16; ++r) pmax = fmaxf(pmax, p1[r]);
;     { auto rr = __builtin_amdgcn_permlane32_swap(__float_as_uint(pmax), __float_as_uint(pmax), false, false);
;       pmax = fmaxf(__uint_as_float(rr[0]), __uint_as_float(rr[1])); }
;     constexpr float C2 = 1.4426950408889634f * SCALE;
;     if (__builtin_expect(__all((pmax - m_reg) * SCALE <= THR), 1)) { mn = m_reg; alpha = 1.f; }
;     else { mn = fmaxf(m_reg, pmax); alpha = __builtin_amdgcn_exp2f((m_reg - mn) * C2); m_reg = mn; }
.LBB0_240:
	v_max3_f32 v194, v114, v115, v116
	v_max3_f32 v195, v117, v118, v119
	v_max3_f32 v196, v120, v121, v122
	v_max3_f32 v197, v123, v124, v125
	v_max3_f32 v194, v194, v126, v127
	v_max3_f32 v195, v195, v128, v129
	v_max3_f32 v196, v196, v98, v99
	v_max3_f32 v197, v197, v100, v101
	v_max3_f32 v194, v194, v102, v103
	v_max3_f32 v195, v195, v104, v105
	v_max3_f32 v196, v196, v106, v107
	v_max3_f32 v197, v197, v108, v109
	v_max3_f32 v194, v194, v110, v111
	v_max3_f32 v195, v195, v112, v113
	v_max3_f32 v194, v194, v195, v196
	v_max_f32_e32 v194, v194, v197
	v_mov_b32_e32 v195, v194
	s_nop 1
	v_permlane32_swap_b32_e32 v194, v195
	v_max_f32_e32 v195, v195, v195
	v_max_f32_e32 v194, v194, v194
	v_max_f32_e32 v221, v194, v195
	v_sub_f32_e32 v194, v221, v217
	v_mul_f32_e32 v194, 0x3db504f3, v194
	v_cmp_ge_f32_e32 vcc, s78, v194
	s_cmp_eq_u64 vcc, exec
	s_cselect_b64 s[4:5], -1, 0
	s_andn2_b64 vcc, exec, s[74:75]
	s_barrier
	s_cbranch_vccnz .LBB0_242
	s_waitcnt vmcnt(0)
	s_waitcnt vmcnt(3)
	ds_write_b128 v1, v[174:177] offset:16384
	s_waitcnt vmcnt(2)
	ds_write_b128 v1, v[170:173] offset:24576
	s_waitcnt vmcnt(1)
	ds_write_b128 v201, v[166:169] offset:49152
	s_waitcnt vmcnt(0)
	ds_write_b128 v201, v[178:181] offset:57344
